# P1 meta-row MFMA side path: batch the 16-24 serialized HBM loads into 3 groups (3 round trips instead of 8-16)
# baseline (speedup 1.0000x reference)
; __global__ void __launch_bounds__(NTHR, 2) fwd_megakernel(Params p) {
;     ...
;             for (int task = bid; task < 114; task += G) {
;                 const bool pair = task >= 112;
;                 const int g0 = pair ? 112 + 2 * (task - 112) : task;
;                 f32x4 c0 = (f32x4){0.f, 0.f, 0.f, 0.f}, c1 = c0;
; #pragma unroll
;                 for (int i = 0; i < 8; ++i) {
;                     const int k = wid * 256 + i * 32 + 8 * fq;
;                     const bf16x8 af = *(const bf16x8*)(XN + (size_t)(16384 + fr) * 2048 + k);
;                     const bf16x8 b0 = *(const bf16x8*)(WinT + (size_t)(g0 * 16 + fr) * 2048 + k);
;                     c0 = __builtin_amdgcn_mfma_f32_16x16x32_bf16(b0, af, c0, 0, 0, 0);
;                     if (pair) { const bf16x8 b1 = *(const bf16x8*)(WinT + (size_t)(g0 * 16 + 16 + fr) * 2048 + k); c1 = __builtin_amdgcn_mfma_f32_16x16x32_bf16(b1, af, c1, 0, 0, 0); }
;                 }
.LBB0_137:
	s_cmpk_gt_i32 s37, 0x6f
	s_cselect_b64 s[20:21], -1, 0
	s_and_b64 s[6:7], s[20:21], exec
	s_cselect_b32 s38, s17, s37
	s_lshl_b32 s12, s38, 4
	v_or_b32_e32 v0, s12, v147
	v_ashrrev_i32_e32 v1, 31, v0
	v_lshlrev_b64 v[0:1], 12, v[0:1]
	v_lshl_add_u64 v[56:57], v[48:49], 0, v[0:1]
	global_load_dwordx4 v[100:103], v[56:57], off
	global_load_dwordx4 v[104:107], v[32:33], off
	global_load_dwordx4 v[112:115], v[56:57], off offset:64
	global_load_dwordx4 v[116:119], v[34:35], off
	global_load_dwordx4 v[124:127], v[56:57], off offset:128
	global_load_dwordx4 v[244:247], v[36:37], off
	v_add_u32_e32 v0, s12, v60
	v_ashrrev_i32_e32 v1, 31, v0
	v_lshlrev_b64 v[0:1], 12, v[0:1]
	s_mov_b32 s9, s8
	v_lshl_add_u64 v[54:55], s[92:93], 0, v[0:1]
	s_mov_b32 s10, s8
	s_mov_b32 s11, s8
	v_mov_b64_e32 v[0:1], s[8:9]
	v_mov_b64_e32 v[2:3], s[10:11]
	v_lshlrev_b32_e32 v58, 1, v16
	v_mov_b32_e32 v59, v19
	v_cndmask_b32_e64 v51, 0, 1, s[20:21]
	v_cmp_ne_u32_e64 s[6:7], 1, v51
	v_lshl_add_u64 v[252:253], v[54:55], 0, v[58:59]
	s_nop 1
	s_and_b64 vcc, exec, s[6:7]
	s_cbranch_vccnz .Lmeta_ld0
	global_load_dwordx4 v[108:111], v[252:253], off
	global_load_dwordx4 v[120:123], v[252:253], off offset:64
	global_load_dwordx4 v[248:251], v[252:253], off offset:128
.Lmeta_ld0:
	s_waitcnt vmcnt(0)
	v_mfma_f32_16x16x32_bf16 v[4:7], v[100:103], v[104:107], 0
	v_mfma_f32_16x16x32_bf16 v[4:7], v[112:115], v[116:119], v[4:7]
	v_mfma_f32_16x16x32_bf16 v[4:7], v[124:127], v[244:247], v[4:7]
	s_cbranch_vccnz .Lmeta_mf0
	v_mfma_f32_16x16x32_bf16 v[0:3], v[108:111], v[104:107], v[0:3]
	v_mfma_f32_16x16x32_bf16 v[0:3], v[120:123], v[116:119], v[0:3]
	v_mfma_f32_16x16x32_bf16 v[0:3], v[248:251], v[244:247], v[0:3]
.Lmeta_mf0:
	global_load_dwordx4 v[100:103], v[56:57], off offset:192
	global_load_dwordx4 v[104:107], v[38:39], off
	global_load_dwordx4 v[112:115], v[56:57], off offset:256
	global_load_dwordx4 v[116:119], v[40:41], off
	global_load_dwordx4 v[124:127], v[56:57], off offset:320
	global_load_dwordx4 v[244:247], v[42:43], off
	s_cbranch_vccnz .Lmeta_ld1
	global_load_dwordx4 v[108:111], v[252:253], off offset:192
	global_load_dwordx4 v[120:123], v[252:253], off offset:256
	global_load_dwordx4 v[248:251], v[252:253], off offset:320
.Lmeta_ld1:
	s_waitcnt vmcnt(0)
	v_mfma_f32_16x16x32_bf16 v[4:7], v[100:103], v[104:107], v[4:7]
	v_mfma_f32_16x16x32_bf16 v[4:7], v[112:115], v[116:119], v[4:7]
	v_mfma_f32_16x16x32_bf16 v[4:7], v[124:127], v[244:247], v[4:7]
	s_cbranch_vccnz .Lmeta_mf1
	v_mfma_f32_16x16x32_bf16 v[0:3], v[108:111], v[104:107], v[0:3]
	v_mfma_f32_16x16x32_bf16 v[0:3], v[120:123], v[116:119], v[0:3]
	v_mfma_f32_16x16x32_bf16 v[0:3], v[248:251], v[244:247], v[0:3]
.Lmeta_mf1:
	global_load_dwordx4 v[100:103], v[56:57], off offset:384
	global_load_dwordx4 v[104:107], v[44:45], off
	global_load_dwordx4 v[112:115], v[56:57], off offset:448
	global_load_dwordx4 v[116:119], v[46:47], off
	s_cbranch_vccnz .Lmeta_ld2
	global_load_dwordx4 v[108:111], v[252:253], off offset:384
	global_load_dwordx4 v[120:123], v[252:253], off offset:448
.Lmeta_ld2:
	s_waitcnt vmcnt(0)
	v_mfma_f32_16x16x32_bf16 v[4:7], v[100:103], v[104:107], v[4:7]
	v_mfma_f32_16x16x32_bf16 v[4:7], v[112:115], v[116:119], v[4:7]
	s_cbranch_vccnz .Lmeta_mf2
	v_mfma_f32_16x16x32_bf16 v[0:3], v[108:111], v[104:107], v[0:3]
	v_mfma_f32_16x16x32_bf16 v[0:3], v[120:123], v[116:119], v[0:3]
.Lmeta_mf2:
	s_nop 7
